# P7 row sums: ds_bpermute butterflies replaced by DPP row adds + permlane16/32 swaps
# baseline (speedup 1.0000x reference)
.Lp7_nopf:
	v_xor_b32_e32 v55, 16, v203
	v_cmp_lt_i32_e32 vcc, v55, v100
	v_xor_b32_e32 v98, 8, v203
	v_xor_b32_e32 v99, 4, v203
	s_mov_b64 s[50:51], -1
	v_lshlrev_b32_e32 v56, 16, v14
	v_and_b32_e32 v57, 0xffff0000, v14
	v_lshlrev_b32_e32 v14, 16, v15
	v_and_b32_e32 v15, 0xffff0000, v15
	v_pk_mul_f32 v[96:97], v[56:57], v[56:57]
	v_pk_mul_f32 v[94:95], v[14:15], v[14:15]
	v_add_f32_e32 v59, v96, v97
	v_lshlrev_b32_e32 v76, 16, v16
	v_and_b32_e32 v77, 0xffff0000, v16
	v_add_f32_e32 v59, v59, v94
	v_pk_mul_f32 v[92:93], v[76:77], v[76:77]
	v_add_f32_e32 v59, v95, v59
	v_lshlrev_b32_e32 v16, 16, v17
	v_and_b32_e32 v17, 0xffff0000, v17
	v_add_f32_e32 v59, v92, v59
	v_pk_mul_f32 v[90:91], v[16:17], v[16:17]
	v_add_f32_e32 v59, v93, v59
	v_lshlrev_b32_e32 v48, 16, v18
	v_and_b32_e32 v49, 0xffff0000, v18
	v_add_f32_e32 v59, v90, v59
	v_lshlrev_b32_e32 v46, 16, v19
	v_and_b32_e32 v47, 0xffff0000, v19
	v_pk_mul_f32 v[18:19], v[48:49], v[48:49]
	v_add_f32_e32 v59, v91, v59
	v_add_f32_e32 v18, v59, v18
	v_lshlrev_b32_e32 v52, 16, v20
	v_and_b32_e32 v53, 0xffff0000, v20
	v_lshlrev_b32_e32 v50, 16, v21
	v_and_b32_e32 v51, 0xffff0000, v21
	v_pk_mul_f32 v[20:21], v[46:47], v[46:47]
	v_add_f32_e32 v18, v19, v18
	v_add_f32_e32 v18, v20, v18
	v_lshlrev_b32_e32 v36, 16, v26
	v_and_b32_e32 v37, 0xffff0000, v26
	v_lshlrev_b32_e32 v34, 16, v27
	v_and_b32_e32 v35, 0xffff0000, v27
	v_lshlrev_b32_e32 v40, 16, v28
	v_and_b32_e32 v41, 0xffff0000, v28
	v_lshlrev_b32_e32 v38, 16, v29
	v_and_b32_e32 v39, 0xffff0000, v29
	v_lshlrev_b32_e32 v28, 16, v42
	v_and_b32_e32 v29, 0xffff0000, v42
	v_lshlrev_b32_e32 v26, 16, v43
	v_and_b32_e32 v27, 0xffff0000, v43
	v_pk_mul_f32 v[42:43], v[52:53], v[52:53]
	v_add_f32_e32 v18, v21, v18
	v_add_f32_e32 v18, v42, v18
	v_lshlrev_b32_e32 v32, 16, v44
	v_and_b32_e32 v33, 0xffff0000, v44
	v_lshlrev_b32_e32 v30, 16, v45
	v_and_b32_e32 v31, 0xffff0000, v45
	v_pk_mul_f32 v[44:45], v[50:51], v[50:51]
	v_add_f32_e32 v18, v43, v18
	v_add_f32_e32 v18, v44, v18
	v_pk_mul_f32 v[60:61], v[36:37], v[36:37]
	v_add_f32_e32 v18, v45, v18
	v_add_f32_e32 v18, v18, v60
	v_pk_mul_f32 v[62:63], v[34:35], v[34:35]
	v_add_f32_e32 v18, v61, v18
	v_add_f32_e32 v18, v62, v18
	v_pk_mul_f32 v[78:79], v[40:41], v[40:41]
	v_add_f32_e32 v18, v63, v18
	v_add_f32_e32 v18, v78, v18
	v_pk_mul_f32 v[80:81], v[38:39], v[38:39]
	v_add_f32_e32 v18, v79, v18
	v_add_f32_e32 v18, v80, v18
	v_pk_mul_f32 v[82:83], v[28:29], v[28:29]
	v_add_f32_e32 v18, v81, v18
	v_add_f32_e32 v18, v18, v82
	v_pk_mul_f32 v[84:85], v[26:27], v[26:27]
	v_add_f32_e32 v18, v83, v18
	v_add_f32_e32 v18, v84, v18
	v_pk_mul_f32 v[86:87], v[32:33], v[32:33]
	v_add_f32_e32 v18, v85, v18
	v_add_f32_e32 v18, v86, v18
	v_pk_mul_f32 v[88:89], v[30:31], v[30:31]
	v_add_f32_e32 v18, v87, v18
	v_add_f32_e32 v18, v88, v18
	v_add_f32_e32 v18, v89, v18
	v_cndmask_b32_e32 v21, v203, v55, vcc
	v_lshlrev_b32_e32 v59, 2, v21
	v_cmp_lt_i32_e32 vcc, v98, v100
	v_xor_b32_e32 v20, 2, v203
	v_add_f32_dpp v18, v18, v18 quad_perm:[1,0,3,2] row_mask:0xf bank_mask:0xf
	v_cndmask_b32_e32 v42, v203, v98, vcc
	v_lshlrev_b32_e32 v60, 2, v42
	v_cmp_lt_i32_e32 vcc, v99, v100
	v_xor_b32_e32 v21, 1, v203
	v_add_f32_dpp v18, v18, v18 quad_perm:[2,3,0,1] row_mask:0xf bank_mask:0xf
	v_cndmask_b32_e32 v43, v203, v99, vcc
	v_lshlrev_b32_e32 v61, 2, v43
	v_cmp_lt_i32_e32 vcc, v20, v100
	v_cndmask_b32_e64 v42, 0, 1, s[6:7]
	v_add_f32_dpp v18, v18, v18 row_half_mirror row_mask:0xf bank_mask:0xf
	v_cndmask_b32_e32 v20, v203, v20, vcc
	v_lshlrev_b32_e32 v62, 2, v20
	v_cmp_lt_i32_e32 vcc, v21, v100
	v_cmp_ne_u32_e64 s[0:1], 1, v42
	v_add_f32_dpp v19, v18, v18 row_mirror row_mask:0xf bank_mask:0xf
	v_cndmask_b32_e32 v18, v203, v21, vcc
	v_lshlrev_b32_e32 v63, 2, v18
	v_lshlrev_b32_e32 v18, 16, v72
	v_and_b32_e32 v21, 0xffff0000, v73
	v_mov_b32_e32 v20, v19
	s_nop 1
	v_permlane16_swap_b32_e32 v19, v20
	s_nop 0
	v_add_f32_e32 v42, v19, v20
	v_and_b32_e32 v19, 0xffff0000, v72
	v_lshlrev_b32_e32 v20, 16, v73
	v_lshlrev_b32_e32 v44, 16, v74
	v_and_b32_e32 v45, 0xffff0000, v74
	v_mov_b32_e32 v43, v42
	s_nop 1
	v_permlane32_swap_b32_e32 v42, v43
	s_nop 0
	v_add_f32_e32 v42, v42, v43
	v_fmamk_f32 v42, v42, 0x3a000000, v199
	v_mul_f32_e32 v43, 0x4b800000, v42
	v_cmp_gt_f32_e32 vcc, s3, v42
	v_lshlrev_b32_e32 v72, 16, v75
	v_and_b32_e32 v73, 0xffff0000, v75
	v_cndmask_b32_e32 v42, v42, v43, vcc
	v_rsq_f32_e32 v42, v42
	s_nop 0
	v_mul_f32_e32 v43, 0x45800000, v42
	v_cndmask_b32_e32 v42, v42, v43, vcc
	v_pk_mul_f32 v[56:57], v[42:43], v[56:57] op_sel_hi:[0,1]
	v_pk_mul_f32 v[74:75], v[42:43], v[76:77] op_sel_hi:[0,1]
	v_pk_mul_f32 v[76:77], v[42:43], v[14:15] op_sel_hi:[0,1]
	v_pk_mul_f32 v[16:17], v[42:43], v[16:17] op_sel_hi:[0,1]
	v_pk_fma_f32 v[18:19], v[136:137], v[56:57], v[18:19]
	v_pk_fma_f32 v[14:15], v[140:141], v[74:75], v[44:45]
	v_pk_fma_f32 v[20:21], v[138:139], v[76:77], v[20:21]
	v_pk_fma_f32 v[16:17], v[142:143], v[16:17], v[72:73]
	s_andn2_b64 vcc, exec, s[6:7]
	s_cbranch_vccnz .LBB0_947
	v_pk_mul_f32 v[44:45], v[18:19], v[18:19]
	v_pk_mul_f32 v[56:57], v[20:21], v[20:21]
	v_add_f32_e32 v43, v44, v45
	v_add_f32_e32 v43, v56, v43
	v_pk_mul_f32 v[64:65], v[14:15], v[14:15]
	v_add_f32_e32 v43, v57, v43
	v_add_f32_e32 v43, v64, v43
	v_pk_mul_f32 v[66:67], v[16:17], v[16:17]
	v_add_f32_e32 v43, v65, v43
	v_add_f32_e32 v43, v66, v43
	v_add_f32_e32 v65, v67, v43
	v_cvt_pk_bf16_f32 v66, v18, v19
	v_cvt_pk_bf16_f32 v67, v20, v21
	v_cvt_pk_bf16_f32 v68, v14, v15
	v_cvt_pk_bf16_f32 v69, v16, v17
	s_mov_b64 s[50:51], 0
	global_store_dwordx4 v[24:25], v[66:69], off

.LBB0_962:
	v_cmp_eq_u32_e32 vcc, 0, v1
	s_nop 1
	v_add_f32_dpp v2, v11, v11 quad_perm:[1,0,3,2] row_mask:0xf bank_mask:0xf
	s_nop 1
	v_add_f32_dpp v2, v2, v2 quad_perm:[2,3,0,1] row_mask:0xf bank_mask:0xf
	s_nop 1
	v_add_f32_dpp v2, v2, v2 row_half_mirror row_mask:0xf bank_mask:0xf
	s_nop 1
	v_add_f32_dpp v2, v2, v2 row_mirror row_mask:0xf bank_mask:0xf
	v_mov_b32_e32 v3, v2
	s_nop 1
	v_permlane16_swap_b32_e32 v2, v3
	s_nop 0
	v_add_f32_e32 v2, v2, v3
	v_mov_b32_e32 v3, v2
	s_nop 1
	v_permlane32_swap_b32_e32 v2, v3
	s_nop 0
	s_and_saveexec_b64 s[0:1], vcc
	s_cbranch_execz .LBB0_943
	s_waitcnt lgkmcnt(0)
	v_add_f32_e32 v1, v2, v3
	v_fmamk_f32 v1, v1, 0x3a000000, v199
	v_mul_f32_e32 v2, 0x4b800000, v1
	v_cmp_gt_f32_e32 vcc, s3, v1
	v_readlane_b32 s28, v230, 3
	v_readlane_b32 s29, v230, 4
	v_cndmask_b32_e32 v1, v1, v2, vcc
	v_rsq_f32_e32 v1, v1
	v_readlane_b32 s30, v230, 5
	v_readlane_b32 s31, v230, 6
	v_mul_f32_e32 v2, 0x45800000, v1
	v_cndmask_b32_e32 v1, v1, v2, vcc
	v_lshl_add_u64 v[2:3], v[22:23], 2, s[28:29]
	global_store_dword v[2:3], v1, off
	s_branch .LBB0_943
